# ada_reduce: last four split-K partial loads issued with the first batch, one counted wait (on top of v45)
# speedup vs baseline: 1.0026x; 1.0026x over previous
; #define TIDX ((wv_ << 6) | lane_id_l())
; #define p (kparams())
; __device__ __forceinline__ void ada_reduce(const int wv_, KPR p) {
;     ...
;   for (int i = blockIdx.x * 512 + TIDX; i < 2 * 5 * 12288; i += gridDim.x * 512) {
;     const int l = i / (5 * 12288), n = i % 12288;
;     float s = p->in[I_BADA][l * 12288 + n];
;     for (int ks = 0; ks < 16; ++ks) s += modp[(size_t)ks * (2 * 5 * 12288) + i];
;     mod[i] = s;
;   }
.LBB0_29:
	v_mul_hi_i32 v2, v0, s3
	v_mul_hi_i32 v3, v0, s15
	v_ashrrev_i32_e32 v1, 31, v0
	v_add_u32_e32 v4, v2, v0
	v_lshrrev_b32_e32 v5, 31, v3
	v_ashrrev_i32_e32 v6, 11, v3
	v_lshlrev_b64 v[2:3], 2, v[0:1]
	v_lshrrev_b32_e32 v1, 31, v4
	v_ashrrev_i32_e32 v7, 15, v4
	v_add_u32_e32 v6, v6, v5
	v_lshl_add_u64 v[4:5], s[6:7], 0, v[2:3]
	v_mul_i32_i24_e32 v29, 0x3000, v6
	v_add_co_u32_e32 v6, vcc, s17, v4
	v_add_u32_e32 v1, v7, v1
	s_nop 0
	v_addc_co_u32_e32 v7, vcc, 0, v5, vcc
	v_add_co_u32_e32 v8, vcc, s18, v4
	v_sub_u32_e32 v31, v0, v29
	s_nop 0
	v_addc_co_u32_e32 v9, vcc, 0, v5, vcc
	v_add_co_u32_e32 v10, vcc, s19, v4
	global_load_dword v30, v[4:5], off
	s_nop 0
	v_addc_co_u32_e32 v11, vcc, 0, v5, vcc
	v_add_co_u32_e32 v12, vcc, s20, v4
	v_add_u32_e32 v0, s14, v0
	s_nop 0
	v_addc_co_u32_e32 v13, vcc, 0, v5, vcc
	v_add_co_u32_e32 v14, vcc, s21, v4
	v_lshl_add_u64 v[2:3], s[12:13], 0, v[2:3]
	s_nop 0
	v_addc_co_u32_e32 v15, vcc, 0, v5, vcc
	v_add_co_u32_e32 v16, vcc, s22, v4
	s_nop 1
	v_addc_co_u32_e32 v17, vcc, 0, v5, vcc
	v_add_co_u32_e32 v18, vcc, s23, v4
	s_nop 1
	v_addc_co_u32_e32 v19, vcc, 0, v5, vcc
	v_add_co_u32_e32 v20, vcc, s24, v4
	s_nop 1
	v_addc_co_u32_e32 v21, vcc, 0, v5, vcc
	v_add_co_u32_e32 v22, vcc, s25, v4
	s_nop 1
	v_addc_co_u32_e32 v23, vcc, 0, v5, vcc
	v_add_co_u32_e32 v24, vcc, s26, v4
	s_nop 1
	v_addc_co_u32_e32 v25, vcc, 0, v5, vcc
	v_add_co_u32_e32 v26, vcc, s27, v4
	s_nop 1
	v_addc_co_u32_e32 v27, vcc, 0, v5, vcc
	global_load_dword v32, v[6:7], off
	global_load_dword v33, v[8:9], off
	global_load_dword v34, v[10:11], off
	global_load_dword v35, v[12:13], off
	global_load_dword v36, v[14:15], off
	global_load_dword v37, v[16:17], off
	global_load_dword v38, v[18:19], off
	global_load_dword v39, v[20:21], off
	global_load_dword v40, v[22:23], off
	global_load_dword v41, v[24:25], off
	global_load_dword v42, v[26:27], off
	v_mad_i32_i24 v8, v1, s16, v31
	v_ashrrev_i32_e32 v9, 31, v8
	v_lshl_add_u64 v[8:9], v[8:9], 2, s[8:9]
	global_load_dword v1, v[8:9], off
	v_add_co_u32_e32 v28, vcc, s28, v4
	s_nop 1
	v_addc_co_u32_e32 v29, vcc, 0, v5, vcc
	v_add_co_u32_e32 v6, vcc, s29, v4
	s_nop 1
	v_addc_co_u32_e32 v7, vcc, 0, v5, vcc
	v_add_co_u32_e32 v8, vcc, s30, v4
	s_nop 1
	v_addc_co_u32_e32 v9, vcc, 0, v5, vcc
	global_load_dword v10, v[28:29], off
	global_load_dword v11, v[6:7], off
	v_add_co_u32_e32 v4, vcc, 0x708000, v4
	s_nop 1
	v_addc_co_u32_e32 v5, vcc, 0, v5, vcc
	global_load_dword v6, v[8:9], off
	global_load_dword v7, v[4:5], off
	s_waitcnt vmcnt(4)
	v_add_f32_e32 v1, v1, v30
	v_add_f32_e32 v1, v1, v32
	v_add_f32_e32 v1, v1, v33
	v_add_f32_e32 v1, v1, v34
	v_add_f32_e32 v1, v1, v35
	v_add_f32_e32 v1, v1, v36
	v_add_f32_e32 v1, v1, v37
	v_add_f32_e32 v1, v1, v38
	v_add_f32_e32 v1, v1, v39
	v_add_f32_e32 v1, v1, v40
	v_add_f32_e32 v1, v1, v41
	v_add_f32_e32 v1, v1, v42
	v_cmp_lt_i32_e32 vcc, s31, v0
	s_or_b64 s[10:11], vcc, s[10:11]
	s_waitcnt vmcnt(3)
	v_add_f32_e32 v1, v1, v10
	s_waitcnt vmcnt(2)
	v_add_f32_e32 v1, v1, v11
	s_waitcnt vmcnt(1)
	v_add_f32_e32 v1, v1, v6
	s_waitcnt vmcnt(0)
	v_add_f32_e32 v1, v1, v7
	global_store_dword v[2:3], v1, off
	s_andn2_b64 exec, exec, s[10:11]
	s_cbranch_execnz .LBB0_29
